# attention unit prologues (windowed and MLA): accumulator zeroing for registers not live in the prologue is issued before the prologue's memory wait instead of after its barrier; on unified zeroless st
# speedup vs baseline: 1.0162x; 1.0117x over previous
.LBB0_514:
	v_readfirstlane_b32 s67, v183
	s_ashr_i32 s69, s67, 6
	s_lshl_b32 s24, s69, 5
	s_and_b32 s65, s24, 0xe0
	v_or_b32_e32 v0, s65, v203
	s_ashr_i32 s24, s67, 9
	v_mul_u32_u24_e32 v0, 0x1800, v0
	v_lshl_add_u64 v[2:3], s[22:23], 0, v[0:1]
	s_mul_i32 s22, s24, 0xc0
	s_ashr_i32 s23, s22, 31
	v_lshl_add_u64 v[2:3], s[22:23], 1, v[2:3]
	v_lshlrev_b32_e32 v0, 1, v182
	v_lshl_add_u64 v[2:3], v[2:3], 0, v[0:1]
	global_load_dwordx4 v[98:101], v[2:3], off
	global_load_dwordx4 v[102:105], v[2:3], off offset:32
	global_load_dwordx4 v[106:109], v[2:3], off offset:64
	global_load_dwordx4 v[110:113], v[2:3], off offset:96
	global_load_dwordx4 v[114:117], v[2:3], off offset:128
	global_load_dwordx4 v[118:121], v[2:3], off offset:160
	global_load_dwordx4 v[122:125], v[2:3], off offset:192
	global_load_dwordx4 v[126:129], v[2:3], off offset:224
	global_load_dwordx4 v[130:133], v[2:3], off offset:256
	global_load_dwordx4 v[134:137], v[2:3], off offset:288
	global_load_dwordx4 v[138:141], v[2:3], off offset:320
	global_load_dwordx4 v[142:145], v[2:3], off offset:352
	v_lshl_add_u64 v[2:3], s[16:17], 0, v[184:185]
	global_load_dwordx4 v[2:5], v[2:3], off
	v_lshl_add_u64 v[6:7], s[16:17], 0, v[186:187]
	global_load_dwordx4 v[6:9], v[6:7], off
	v_lshl_add_u64 v[10:11], s[18:19], 0, v[188:189]
	v_lshl_add_u64 v[14:15], s[20:21], 0, v[184:185]
	global_load_dwordx4 v[10:13], v[10:11], off
	v_lshl_add_u64 v[18:19], s[20:21], 0, v[186:187]
	global_load_dwordx4 v[14:17], v[14:15], off
	v_lshl_add_u64 v[22:23], s[16:17], 0, v[190:191]
	global_load_dwordx4 v[18:21], v[18:19], off
	v_lshl_add_u64 v[26:27], s[16:17], 0, v[192:193]
	global_load_dwordx4 v[22:25], v[22:23], off
	v_lshl_add_u64 v[30:31], s[18:19], 0, v[222:223]
	global_load_dwordx4 v[26:29], v[26:27], off
	v_lshl_add_u64 v[34:35], s[20:21], 0, v[190:191]
	global_load_dwordx4 v[30:33], v[30:31], off
	v_lshl_add_u64 v[38:39], s[20:21], 0, v[192:193]
	global_load_dwordx4 v[34:37], v[34:35], off
	v_add_u32_e32 v0, v202, v218
	global_load_dwordx4 v[38:41], v[38:39], off
	s_and_b32 s22, s67, 0xffffff00
	s_cmpk_eq_i32 s22, 0x100
	s_cselect_b64 s[24:25], -1, 0
	s_cmpk_lg_i32 s22, 0x100
	s_cselect_b64 s[26:27], -1, 0
	v_mov_b64_e32 v[236:237], 0xff
	s_and_b64 vcc, exec, s[26:27]
	v_mov_b32_e32 v42, v1
	v_mov_b32_e32 v43, v1
	v_mov_b32_e32 v44, v1
	v_mov_b32_e32 v45, v1
	v_mov_b32_e32 v46, v1
	v_mov_b32_e32 v47, v1
	v_mov_b32_e32 v48, v1
	v_mov_b32_e32 v49, v1
	v_mov_b32_e32 v50, v1
	v_mov_b32_e32 v51, v1
	v_mov_b32_e32 v52, v1
	v_mov_b32_e32 v53, v1
	v_mov_b32_e32 v54, v1
	v_mov_b32_e32 v55, v1
	v_mov_b32_e32 v56, v1
	v_mov_b32_e32 v57, v1
	v_mov_b32_e32 v58, v1
	v_mov_b32_e32 v59, v1
	v_mov_b32_e32 v60, v1
	v_mov_b32_e32 v61, v1
	v_mov_b32_e32 v62, v1
	v_mov_b32_e32 v63, v1
	v_mov_b32_e32 v64, v1
	v_mov_b32_e32 v65, v1
	v_mov_b32_e32 v66, v1
	v_mov_b32_e32 v67, v1
	v_mov_b32_e32 v68, v1
	v_mov_b32_e32 v69, v1
	v_mov_b32_e32 v70, v1
	v_mov_b32_e32 v71, v1
	v_mov_b32_e32 v72, v1
	v_mov_b32_e32 v73, v1
	v_mov_b32_e32 v74, v1
	v_mov_b32_e32 v75, v1
	v_mov_b32_e32 v76, v1
	v_mov_b32_e32 v77, v1
	v_mov_b32_e32 v78, v1
	v_mov_b32_e32 v79, v1
	v_mov_b32_e32 v80, v1
	v_mov_b32_e32 v81, v1
	v_mov_b32_e32 v82, v1
	v_mov_b32_e32 v83, v1
	v_mov_b32_e32 v84, v1
	v_mov_b32_e32 v85, v1
	v_mov_b32_e32 v86, v1
	v_mov_b32_e32 v87, v1
	v_mov_b32_e32 v88, v1
	v_mov_b32_e32 v89, v1
	v_mov_b32_e32 v90, v1
	v_mov_b32_e32 v91, v1
	v_mov_b32_e32 v92, v1
	v_mov_b32_e32 v93, v1
	v_mov_b32_e32 v94, v1
	v_mov_b32_e32 v95, v1
	v_mov_b32_e32 v96, v1
	v_mov_b32_e32 v97, v1
	v_mov_b32_e32 v239, v1
	v_mov_b32_e32 v240, v1
	s_waitcnt vmcnt(0)
	ds_write_b128 v0, v[2:5]
	v_add_u32_e32 v0, v198, v220
	ds_write_b128 v0, v[6:9]
	ds_write_b128 v234, v[10:13] offset:256
	v_add_u32_e32 v0, v200, v218
	v_lshl_add_u64 v[2:3], s[16:17], 0, v[210:211]
	ds_write_b128 v0, v[14:17] offset:25600
	v_add_u32_e32 v0, v208, v220
	ds_write_b128 v0, v[18:21] offset:25600
	ds_write_b128 v235, v[22:25] offset:46080
	ds_write_b128 v224, v[26:29] offset:46080
	ds_write_b128 v234, v[30:33] offset:46336
	ds_write_b128 v254, v[34:37]
	ds_write_b128 v238, v[38:41]
	global_load_dwordx4 v[146:149], v[2:3], off
	v_lshl_add_u64 v[2:3], s[16:17], 0, v[212:213]
	global_load_dwordx4 v[150:153], v[2:3], off
	v_lshl_add_u64 v[2:3], s[18:19], 0, v[214:215]
	global_load_dwordx4 v[154:157], v[2:3], off
	v_lshl_add_u64 v[2:3], s[20:21], 0, v[210:211]
	global_load_dwordx4 v[158:161], v[2:3], off
	v_lshl_add_u64 v[2:3], s[20:21], 0, v[212:213]
	global_load_dwordx4 v[162:165], v[2:3], off
	s_waitcnt lgkmcnt(0)
	s_barrier
	s_cbranch_vccnz .LBB0_516
	s_setprio 1
.LBB0_516:
	s_add_i32 s70, s68, s28
	s_lshl_b32 s30, s70, 1
	s_cmp_gt_u32 s69, 3
	s_cselect_b64 s[28:29], -1, 0
	v_cndmask_b32_e64 v0, 0, 1, s[28:29]
	v_or_b32_e32 v217, s30, v0
	v_mov_b32_e32 v0, v1
	v_mov_b32_e32 v2, v1
	v_mov_b32_e32 v3, v1
	v_mov_b32_e32 v4, v1
	v_mov_b32_e32 v5, v1
	v_mov_b32_e32 v6, v1
	v_mov_b32_e32 v7, v1
	v_mov_b32_e32 v8, v1
	v_mov_b32_e32 v9, v1
	v_mov_b32_e32 v10, v1
	v_mov_b32_e32 v11, v1
	v_mov_b32_e32 v12, v1
	v_mov_b32_e32 v13, v1
	v_mov_b32_e32 v14, v1
	v_mov_b32_e32 v15, v1
	v_mov_b32_e32 v16, v1
	v_mov_b32_e32 v17, v1
	v_mov_b32_e32 v18, v1
	v_mov_b32_e32 v19, v1
	v_mov_b32_e32 v20, v1
	v_mov_b32_e32 v21, v1
	v_mov_b32_e32 v22, v1
	v_mov_b32_e32 v23, v1
	v_mov_b32_e32 v24, v1
	v_mov_b32_e32 v25, v1
	v_mov_b32_e32 v26, v1
	v_mov_b32_e32 v27, v1
	v_mov_b32_e32 v28, v1
	v_mov_b32_e32 v29, v1
	v_mov_b32_e32 v30, v1
	v_mov_b32_e32 v31, v1
	v_mov_b32_e32 v32, v1
	v_mov_b32_e32 v33, v1
	v_mov_b32_e32 v34, v1
	v_mov_b32_e32 v35, v1
	v_mov_b32_e32 v36, v1
	v_mov_b32_e32 v37, v1
	v_mov_b32_e32 v38, v1
	v_mov_b32_e32 v39, v1
	v_mov_b32_e32 v40, v1
	v_mov_b32_e32 v41, v1
	s_cmp_lt_u32 s69, 4
	s_cselect_b64 s[22:23], -1, 0
	s_mov_b32 s71, 0
	s_cmp_gt_u32 s69, 3
	s_cselect_b32 s100, 1, 0
	s_cselect_b32 s99, -1, 0
	s_mov_b32 s98, 0
	s_branch .LBB0_518

.LBB0_788:
	v_lshl_add_u64 v[4:5], s[14:15], 0, v[106:107]
	global_load_dwordx4 v[96:99], v[4:5], off
	v_lshl_add_u64 v[4:5], s[16:17], 0, v[106:107]
	v_lshl_add_u64 v[8:9], s[16:17], 0, v[108:109]
	global_load_dwordx4 v[100:103], v[4:5], off
	v_add_u32_e32 v0, v122, v120
	global_load_dwordx4 v[8:11], v[8:9], off
	v_lshl_add_u64 v[4:5], s[14:15], 0, v[108:109]
	global_load_dwordx4 v[4:7], v[4:5], off
	s_cmp_lt_i32 s72, 3
	v_mov_b32_e32 v3, v1
	v_mov_b32_e32 v12, v1
	v_mov_b32_e32 v13, v1
	v_mov_b32_e32 v14, v1
	v_mov_b32_e32 v15, v1
	v_mov_b32_e32 v16, v1
	v_mov_b32_e32 v17, v1
	v_mov_b32_e32 v18, v1
	v_mov_b32_e32 v19, v1
	v_mov_b32_e32 v20, v1
	v_mov_b32_e32 v21, v1
	v_mov_b32_e32 v22, v1
	v_mov_b32_e32 v23, v1
	v_mov_b32_e32 v24, v1
	v_mov_b32_e32 v25, v1
	v_mov_b32_e32 v26, v1
	v_mov_b32_e32 v27, v1
	v_mov_b32_e32 v28, v1
	v_mov_b32_e32 v29, v1
	v_mov_b32_e32 v30, v1
	v_mov_b32_e32 v31, v1
	v_mov_b32_e32 v32, v1
	v_mov_b32_e32 v33, v1
	v_mov_b32_e32 v34, v1
	v_mov_b32_e32 v35, v1
	v_mov_b32_e32 v36, v1
	v_mov_b32_e32 v37, v1
	v_mov_b32_e32 v38, v1
	v_mov_b32_e32 v39, v1
	v_mov_b32_e32 v40, v1
	v_mov_b32_e32 v41, v1
	v_mov_b32_e32 v42, v1
	v_mov_b32_e32 v43, v1
	v_mov_b32_e32 v44, v1
	v_mov_b32_e32 v45, v1
	v_mov_b32_e32 v46, v1
	v_mov_b32_e32 v47, v1
	v_mov_b32_e32 v48, v1
	v_mov_b32_e32 v49, v1
	v_mov_b32_e32 v50, v1
	v_mov_b32_e32 v51, v1
	v_mov_b32_e32 v52, v1
	v_mov_b32_e32 v53, v1
	v_mov_b32_e32 v54, v1
	v_mov_b32_e32 v55, v1
	v_mov_b32_e32 v56, v1
	v_mov_b32_e32 v57, v1
	v_mov_b32_e32 v58, v1
	v_mov_b32_e32 v59, v1
	v_mov_b32_e32 v60, v1
	v_mov_b32_e32 v61, v1
	v_mov_b32_e32 v62, v1
	v_mov_b32_e32 v63, v1
	v_mov_b32_e32 v64, v1
	v_mov_b32_e32 v65, v1
	v_mov_b32_e32 v66, v1
	v_mov_b32_e32 v67, v1
	v_mov_b32_e32 v68, v1
	v_mov_b32_e32 v69, v1
	v_mov_b32_e32 v70, v1
	v_mov_b32_e32 v71, v1
	v_mov_b32_e32 v72, v1
	v_mov_b32_e32 v73, v1
	v_mov_b32_e32 v74, v1
	v_mov_b32_e32 v75, v1
	v_mov_b32_e32 v76, v1
	v_mov_b32_e32 v77, v1
	v_mov_b32_e32 v78, v1
	v_mov_b32_e32 v79, v1
	s_waitcnt vmcnt(0)
	v_mul_f32_e32 v134, 0x3fb8aa3b, v134
	ds_write_b128 v0, v[96:99]
	v_add_u32_e32 v0, v110, v120
	ds_write_b128 v0, v[100:103] offset:9216
	v_add_u32_e32 v0, v112, v120
	ds_write_b128 v0, v[4:7] offset:21504
	ds_write_b128 v133, v[8:11] offset:30720
	s_cbranch_scc1 .LBB0_790
	v_lshl_add_u64 v[4:5], s[14:15], 0, v[114:115]
	global_load_dwordx4 v[96:99], v[4:5], off
	v_lshl_add_u64 v[4:5], s[16:17], 0, v[114:115]
	global_load_dwordx4 v[100:103], v[4:5], off

.LBB0_792:
	s_lshl_b32 s29, s72, 1
	s_cmp_gt_u32 s71, 3
	s_cselect_b64 s[26:27], -1, 0
	v_cndmask_b32_e64 v0, 0, 1, s[26:27]
	s_cmp_lt_u32 s71, 4
	v_readfirstlane_b32 s30, v0
	s_cselect_b64 s[18:19], -1, 0
	s_or_b32 s73, s29, s30
	s_cmp_lt_i32 s73, 1
	s_cbranch_scc1 .LBB0_815
	v_or_b32_e32 v0, s28, v2
	v_sub_u32_e32 v135, v124, v0
	v_mov_b32_e32 v0, v1
	v_mov_b32_e32 v2, v1
	v_mov_b32_e32 v4, v1
	v_mov_b32_e32 v5, v1
	v_mov_b32_e32 v6, v1
	v_mov_b32_e32 v7, v1
	v_mov_b32_e32 v8, v1
	v_mov_b32_e32 v9, v1
	v_mov_b32_e32 v10, v1
	v_mov_b32_e32 v11, v1
	s_mov_b32 s77, 0
	s_cmp_gt_u32 s71, 3
	s_cselect_b32 s100, 1, 0
	s_cselect_b32 s99, -1, 0
	s_mov_b32 s98, 0
	s_branch .LBB0_795
